# v8 plus: branch-projection loop without the redundant A-half DMA (counted waits re-derived), phase-1 S5 deal 3+1, carry counted wait
# speedup vs baseline: 1.0099x; 1.0099x over previous
; #define PG8_STAGE(...) PG8_STAGE_(__VA_ARGS__, 0u)
; #define PG8_WAIT_V(n) asm volatile("s_waitcnt vmcnt(" #n ")" ::: "memory")
; #define PG8_WAIT_L(n) asm volatile("s_waitcnt lgkmcnt(" #n ")" ::: "memory")
; #define PG8_BAR __builtin_amdgcn_s_barrier()
; #define PG8_SCHED __builtin_amdgcn_sched_barrier(0)
; template <class Epi, class Sched, bool ALIGN_EPI = true, bool SP2 = true>
; __device__ __forceinline__ void gemm_phase(LAS unsigned char* lds, const Gemm g, const Sched& S, const Epi& E) {
;     ...
;             PG8_LDB(B0, 0, 0); PG8_LDB(B1, 0, 1); PG8_SCHED; PG8_LDA(At, 0, 0); PG8_STAGE(PG8_SA(1, 1), a1, voffAh);
;             PG8_WAIT_V(8); PG8_WAIT_L(0); PG8_BAR; PG8_MMA(0, 0, At, B0); PG8_MMA(0, 1, At, B1); PG8_BAR; PG8_SCHED;
;             if constexpr (!Epi::HALF_M) PG8_LDA(At, 0, 1); PG8_STAGE(PG8_SB(0, 0), b2, voffB); PG8_STAGE(PG8_SB(0, 1), b2, voffBh); PG8_STAGE(PG8_SA(0, 0), a2, voffA);
;             PG8_WAIT_V(8); PG8_WAIT_L(0); PG8_BAR; if constexpr (!Epi::HALF_M) { PG8_MMA(1, 0, At, B0); PG8_MMA(1, 1, At, B1); } PG8_BAR; PG8_SCHED;
.LBB0_1336:
	v_add_u32_e32 v34, s27, v174
	ds_read_b128 v[148:151], v34
	ds_read_b128 v[152:155], v34 offset:1024
	ds_read_b128 v[156:159], v34 offset:2048
	ds_read_b128 v[160:163], v34 offset:3072
	v_add_u32_e32 v34, s30, v174
	ds_read_b128 v[178:181], v34
	ds_read_b128 v[182:185], v34 offset:1024
	ds_read_b128 v[186:189], v34 offset:2048
	ds_read_b128 v[190:193], v34 offset:3072
	s_add_i32 s64, s18, 2
	s_add_u32 s20, s0, 0x80
	s_addc_u32 s19, s1, 0
	s_cmp_eq_u32 s51, s18
	s_cselect_b32 s18, s59, s20
	s_cselect_b32 s19, s3, s19
	s_cselect_b32 s21, s60, s63
	s_cselect_b32 s20, s61, s62
	v_mov_b32_e32 v34, v166
	ds_read_b128 v[206:209], v176
	ds_read_b128 v[210:213], v176 offset:1024
	ds_read_b128 v[214:217], v176 offset:2048
	ds_read_b128 v[218:221], v176 offset:3072
	ds_read_b128 v[222:225], v176 offset:4096
	ds_read_b128 v[242:245], v176 offset:5120
	ds_read_b128 v[246:249], v176 offset:6144
	ds_read_b128 v[250:253], v176 offset:7168
	s_add_i32 m0, s34, 0xc000
	s_nop 0
	v_mov_b32_e32 v34, v168
	s_add_i32 m0, s34, 0xe000
	s_nop 0
	s_waitcnt vmcnt(6)
	s_waitcnt lgkmcnt(0)
	s_barrier
	s_setprio 1
	s_waitcnt lgkmcnt(0)
	v_mfma_f32_16x16x32_bf16 v[144:147], v[148:151], v[206:209], v[144:147]
	v_mfma_f32_16x16x32_bf16 v[140:143], v[156:159], v[206:209], v[140:143]
	v_mfma_f32_16x16x32_bf16 v[128:131], v[148:151], v[214:217], v[128:131]
	v_mfma_f32_16x16x32_bf16 v[124:127], v[156:159], v[214:217], v[124:127]
	v_mfma_f32_16x16x32_bf16 v[112:115], v[148:151], v[222:225], v[112:115]
	v_mfma_f32_16x16x32_bf16 v[108:111], v[156:159], v[222:225], v[108:111]
	v_mfma_f32_16x16x32_bf16 v[96:99], v[148:151], v[246:249], v[96:99]
	v_mfma_f32_16x16x32_bf16 v[92:95], v[156:159], v[246:249], v[92:95]
	v_mfma_f32_16x16x32_bf16 v[144:147], v[152:155], v[210:213], v[144:147]
	v_mfma_f32_16x16x32_bf16 v[140:143], v[160:163], v[210:213], v[140:143]
	v_mfma_f32_16x16x32_bf16 v[128:131], v[152:155], v[218:221], v[128:131]
	v_mfma_f32_16x16x32_bf16 v[124:127], v[160:163], v[218:221], v[124:127]
	v_mfma_f32_16x16x32_bf16 v[112:115], v[152:155], v[242:245], v[112:115]
	v_mfma_f32_16x16x32_bf16 v[108:111], v[160:163], v[242:245], v[108:111]
	v_mfma_f32_16x16x32_bf16 v[96:99], v[152:155], v[250:253], v[96:99]
	v_mfma_f32_16x16x32_bf16 v[92:95], v[160:163], v[250:253], v[92:95]
	s_setprio 0
	s_setprio 1
	v_mfma_f32_16x16x32_bf16 v[136:139], v[178:181], v[206:209], v[136:139]
	v_mfma_f32_16x16x32_bf16 v[132:135], v[186:189], v[206:209], v[132:135]
	v_mfma_f32_16x16x32_bf16 v[120:123], v[178:181], v[214:217], v[120:123]
	v_mfma_f32_16x16x32_bf16 v[116:119], v[186:189], v[214:217], v[116:119]
	v_mfma_f32_16x16x32_bf16 v[104:107], v[178:181], v[222:225], v[104:107]
	v_mfma_f32_16x16x32_bf16 v[100:103], v[186:189], v[222:225], v[100:103]
	v_mfma_f32_16x16x32_bf16 v[88:91], v[178:181], v[246:249], v[88:91]
	v_mfma_f32_16x16x32_bf16 v[84:87], v[186:189], v[246:249], v[84:87]
	v_mfma_f32_16x16x32_bf16 v[136:139], v[182:185], v[210:213], v[136:139]
	v_mfma_f32_16x16x32_bf16 v[132:135], v[190:193], v[210:213], v[132:135]
	v_mfma_f32_16x16x32_bf16 v[120:123], v[182:185], v[218:221], v[120:123]
	v_mfma_f32_16x16x32_bf16 v[116:119], v[190:193], v[218:221], v[116:119]
	v_mfma_f32_16x16x32_bf16 v[104:107], v[182:185], v[242:245], v[104:107]
	v_mfma_f32_16x16x32_bf16 v[100:103], v[190:193], v[242:245], v[100:103]
	v_mfma_f32_16x16x32_bf16 v[88:91], v[182:185], v[250:253], v[88:91]
	v_mfma_f32_16x16x32_bf16 v[84:87], v[190:193], v[250:253], v[84:87]
	s_setprio 0
	s_barrier
	v_mov_b32_e32 v34, v167
	s_mov_b32 m0, s28
	s_nop 0
	global_load_lds_dwordx4 v34, s[20:21]
	v_mov_b32_e32 v34, v169
	s_mov_b32 m0, s29
	s_nop 0
	global_load_lds_dwordx4 v34, s[20:21]
	v_mov_b32_e32 v34, v170
	s_mov_b32 m0, s31
	s_nop 0
	global_load_lds_dwordx4 v34, s[20:21]
	v_mov_b32_e32 v34, v171
	s_mov_b32 m0, s33
	s_nop 0
	global_load_lds_dwordx4 v34, s[20:21]
	v_mov_b32_e32 v34, v166
	s_mov_b32 m0, s34
	s_nop 0
	global_load_lds_dwordx4 v34, s[18:19]
	v_mov_b32_e32 v34, v168
	s_mov_b32 m0, s35
	s_nop 0
	global_load_lds_dwordx4 v34, s[18:19]
	s_waitcnt vmcnt(6)
	s_waitcnt lgkmcnt(0)
	s_barrier
	s_barrier
; #define PG8_STAGE(...) PG8_STAGE_(__VA_ARGS__, 0u)
; #define PG8_WAIT_V(n) asm volatile("s_waitcnt vmcnt(" #n ")" ::: "memory")
; #define PG8_WAIT_L(n) asm volatile("s_waitcnt lgkmcnt(" #n ")" ::: "memory")
; #define PG8_BAR __builtin_amdgcn_s_barrier()
; #define PG8_SCHED __builtin_amdgcn_sched_barrier(0)
; template <class Epi, class Sched, bool ALIGN_EPI = true, bool SP2 = true>
; __device__ __forceinline__ void gemm_phase(LAS unsigned char* lds, const Gemm g, const Sched& S, const Epi& E) {
;     ...
;         for (int t = 0; t < nt; t += 2) {
;             const bool last = (t == nt - 2);
;             const char* a1 = cA + (size_t)(t + 1) * kstep;
;             const char* a2 = last ? nA : cA + (size_t)(t + 2) * kstep; const char* b2 = last ? nB : cB + (size_t)(t + 2) * kstep;
;             const char* a3 = a2 + kstep; const char* b3 = b2 + kstep;
;     ...
;             PG8_LDB(B0, 1, 0); PG8_LDB(B1, 1, 1); PG8_SCHED; PG8_LDA(At, 1, 0); PG8_STAGE(PG8_SA(0, 1), a2, voffAh);
;             PG8_WAIT_V(8); PG8_WAIT_L(0); PG8_BAR; PG8_MMA(0, 0, At, B0); PG8_MMA(0, 1, At, B1); PG8_BAR; PG8_SCHED;
;             if constexpr (!Epi::HALF_M) PG8_LDA(At, 1, 1); PG8_STAGE(PG8_SB(1, 0), b3, voffB); PG8_STAGE(PG8_SB(1, 1), b3, voffBh); PG8_STAGE(PG8_SA(1, 0), a3, voffA);
;             PG8_WAIT_V(8); PG8_WAIT_L(0); PG8_BAR; if constexpr (!Epi::HALF_M) { PG8_MMA(1, 0, At, B0); PG8_MMA(1, 1, At, B1); } PG8_BAR; PG8_SCHED;
	v_add_u32_e32 v34, s41, v174
	ds_read_b128 v[148:151], v34
	ds_read_b128 v[152:155], v34 offset:1024
	ds_read_b128 v[156:159], v34 offset:2048
	ds_read_b128 v[160:163], v34 offset:3072
	v_add_u32_e32 v34, s46, v174
	ds_read_b128 v[178:181], v34
	ds_read_b128 v[182:185], v34 offset:1024
	ds_read_b128 v[186:189], v34 offset:2048
	ds_read_b128 v[190:193], v34 offset:3072
	v_mov_b32_e32 v34, v166
	s_mov_b32 m0, s36
	ds_read_b128 v[206:209], v176 offset:32768
	ds_read_b128 v[210:213], v176 offset:33792
	ds_read_b128 v[214:217], v176 offset:34816
	ds_read_b128 v[218:221], v176 offset:35840
	ds_read_b128 v[222:225], v176 offset:36864
	ds_read_b128 v[242:245], v176 offset:37888
	ds_read_b128 v[246:249], v176 offset:38912
	ds_read_b128 v[250:253], v176 offset:39936
	s_nop 0
	v_mov_b32_e32 v34, v168
	s_mov_b32 m0, s37
	s_nop 0
	s_waitcnt vmcnt(6)
	s_waitcnt lgkmcnt(0)
	s_barrier
	s_setprio 1
	s_waitcnt lgkmcnt(0)
	v_mfma_f32_16x16x32_bf16 v[144:147], v[148:151], v[206:209], v[144:147]
	v_mfma_f32_16x16x32_bf16 v[140:143], v[156:159], v[206:209], v[140:143]
	v_mfma_f32_16x16x32_bf16 v[128:131], v[148:151], v[214:217], v[128:131]
	v_mfma_f32_16x16x32_bf16 v[124:127], v[156:159], v[214:217], v[124:127]
	v_mfma_f32_16x16x32_bf16 v[112:115], v[148:151], v[222:225], v[112:115]
	v_mfma_f32_16x16x32_bf16 v[108:111], v[156:159], v[222:225], v[108:111]
	v_mfma_f32_16x16x32_bf16 v[96:99], v[148:151], v[246:249], v[96:99]
	v_mfma_f32_16x16x32_bf16 v[92:95], v[156:159], v[246:249], v[92:95]
	v_mfma_f32_16x16x32_bf16 v[144:147], v[152:155], v[210:213], v[144:147]
	v_mfma_f32_16x16x32_bf16 v[140:143], v[160:163], v[210:213], v[140:143]
	v_mfma_f32_16x16x32_bf16 v[128:131], v[152:155], v[218:221], v[128:131]
	v_mfma_f32_16x16x32_bf16 v[124:127], v[160:163], v[218:221], v[124:127]
	v_mfma_f32_16x16x32_bf16 v[112:115], v[152:155], v[242:245], v[112:115]
	v_mfma_f32_16x16x32_bf16 v[108:111], v[160:163], v[242:245], v[108:111]
	v_mfma_f32_16x16x32_bf16 v[96:99], v[152:155], v[250:253], v[96:99]
	v_mfma_f32_16x16x32_bf16 v[92:95], v[160:163], v[250:253], v[92:95]
	s_setprio 0
	s_setprio 1
	v_mfma_f32_16x16x32_bf16 v[136:139], v[178:181], v[206:209], v[136:139]
	v_mfma_f32_16x16x32_bf16 v[132:135], v[186:189], v[206:209], v[132:135]
	v_mfma_f32_16x16x32_bf16 v[120:123], v[178:181], v[214:217], v[120:123]
	v_mfma_f32_16x16x32_bf16 v[116:119], v[186:189], v[214:217], v[116:119]
	v_mfma_f32_16x16x32_bf16 v[104:107], v[178:181], v[222:225], v[104:107]
	v_mfma_f32_16x16x32_bf16 v[100:103], v[186:189], v[222:225], v[100:103]
	v_mfma_f32_16x16x32_bf16 v[88:91], v[178:181], v[246:249], v[88:91]
	v_mfma_f32_16x16x32_bf16 v[84:87], v[186:189], v[246:249], v[84:87]
	v_mfma_f32_16x16x32_bf16 v[136:139], v[182:185], v[210:213], v[136:139]
	v_mfma_f32_16x16x32_bf16 v[132:135], v[190:193], v[210:213], v[132:135]
	v_mfma_f32_16x16x32_bf16 v[120:123], v[182:185], v[218:221], v[120:123]
	v_mfma_f32_16x16x32_bf16 v[116:119], v[190:193], v[218:221], v[116:119]
	v_mfma_f32_16x16x32_bf16 v[104:107], v[182:185], v[242:245], v[104:107]
	v_mfma_f32_16x16x32_bf16 v[100:103], v[190:193], v[242:245], v[100:103]
	v_mfma_f32_16x16x32_bf16 v[88:91], v[182:185], v[250:253], v[88:91]
	v_mfma_f32_16x16x32_bf16 v[84:87], v[190:193], v[250:253], v[84:87]
	s_setprio 0
	s_barrier
	v_mov_b32_e32 v34, v167
	s_mov_b32 m0, s42
	v_lshl_add_u64 v[148:149], s[20:21], 0, v[34:35]
	v_lshl_add_u64 v[148:149], v[148:149], 0, s[80:81]
	v_mov_b32_e32 v34, v169
	global_load_lds_dwordx4 v[148:149], off
	s_mov_b32 m0, s43
	v_lshl_add_u64 v[148:149], s[20:21], 0, v[34:35]
	v_lshl_add_u64 v[148:149], v[148:149], 0, s[80:81]
	v_mov_b32_e32 v34, v170
	global_load_lds_dwordx4 v[148:149], off
	s_mov_b32 m0, s47
	v_lshl_add_u64 v[148:149], s[20:21], 0, v[34:35]
	v_lshl_add_u64 v[148:149], v[148:149], 0, s[80:81]
	v_mov_b32_e32 v34, v171
	global_load_lds_dwordx4 v[148:149], off
	s_mov_b32 m0, s48
	v_lshl_add_u64 v[148:149], s[20:21], 0, v[34:35]
	v_lshl_add_u64 v[148:149], v[148:149], 0, s[80:81]
	v_mov_b32_e32 v34, v166
	global_load_lds_dwordx4 v[148:149], off
	s_mov_b32 m0, s44
	v_lshl_add_u64 v[148:149], s[18:19], 0, v[34:35]
	v_lshl_add_u64 v[148:149], v[148:149], 0, s[80:81]
	v_mov_b32_e32 v34, v168
	global_load_lds_dwordx4 v[148:149], off
	s_mov_b32 m0, s45
	v_lshl_add_u64 v[148:149], s[18:19], 0, v[34:35]
	v_lshl_add_u64 v[148:149], v[148:149], 0, s[80:81]
	global_load_lds_dwordx4 v[148:149], off
	s_waitcnt vmcnt(6)
	s_waitcnt lgkmcnt(0)
	s_barrier
	s_barrier
	s_add_u32 s0, s0, 0x100
	s_addc_u32 s1, s1, 0
	s_add_u32 s62, s62, 0x100
	s_addc_u32 s63, s63, 0
	s_cmp_ge_i32 s64, s49
	s_mov_b32 s18, s64
	s_cbranch_scc0 .LBB0_1336
